# ssd_out closing gated-norm pass software-pipelined: next batch's loads in flight while the current batch is scaled and stored
# baseline (speedup 1.0000x reference)
; DI unsigned pk2(float lo, float hi) { unsigned r; asm volatile("v_cvt_pk_bf16_f32 %0, %1, %2" : "=v"(r) : "v"(lo), "v"(hi)); return r; }
; DI float bflo(unsigned u) { return __uint_as_float(u << 16); }
; DI float bfhi(unsigned u) { return __uint_as_float(u & 0xffff0000u); }
; DI void ssd_out_unit(const Params& p, int layer, int hf, int bl, int c, unsigned char* shm, int tid, bool dry = false) {
;     ...
;   bf16_t* zr = projb + (size_t)(c * 128 + i_row) * NP + C_Z + 4 * fq;
;   for (int t0 = 0; t0 < 64; t0 += 8) {
;     uint2 v8[8]; float4 g8[8];
; #pragma unroll
;     for (int q = 0; q < 8; ++q) { v8[q] = *(const uint2*)(zr + 16 * (t0 + q)); g8[q] = *(const float4*)(gn + 16 * (t0 + q) + 4 * fq); }
; #pragma unroll
;     for (int q = 0; q < 8; ++q) {
;       uint2 w; w.x = pk2(bflo(v8[q].x) * rinv * g8[q].x, bfhi(v8[q].x) * rinv * g8[q].y); w.y = pk2(bflo(v8[q].y) * rinv * g8[q].z, bfhi(v8[q].y) * rinv * g8[q].w);
;       *(uint2*)(zr + 16 * (t0 + q)) = w;
;     }
;   }
.LBB0_570:
	v_lshl_add_u64 v[248:249], s[0:1], 0, v[160:161]
	global_load_dwordx2 v[144:145], v[20:21], off offset:-228
	global_load_dwordx4 v[172:175], v[248:249], off offset:-460
	global_load_dwordx2 v[146:147], v[20:21], off offset:-196
	global_load_dwordx4 v[176:179], v[248:249], off offset:-396
	global_load_dwordx2 v[148:149], v[20:21], off offset:-164
	global_load_dwordx4 v[180:183], v[248:249], off offset:-332
	global_load_dwordx2 v[150:151], v[20:21], off offset:-132
	global_load_dwordx4 v[184:187], v[248:249], off offset:-268
	global_load_dwordx2 v[152:153], v[20:21], off offset:-100
	global_load_dwordx4 v[188:191], v[248:249], off offset:-204
	global_load_dwordx2 v[154:155], v[20:21], off offset:-68
	global_load_dwordx4 v[236:239], v[248:249], off offset:-140
	global_load_dwordx2 v[156:157], v[20:21], off offset:-36
	global_load_dwordx4 v[240:243], v[248:249], off offset:-76
	global_load_dwordx2 v[158:159], v[20:21], off offset:-4
	global_load_dwordx4 v[244:247], v[248:249], off offset:-12
	global_load_dwordx2 v[22:23], v[20:21], off offset:28
	global_load_dwordx4 v[0:3], v[248:249], off offset:52
	global_load_dwordx2 v[24:25], v[20:21], off offset:60
	global_load_dwordx4 v[4:7], v[248:249], off offset:116
	global_load_dwordx2 v[26:27], v[20:21], off offset:92
	global_load_dwordx4 v[8:11], v[248:249], off offset:180
	global_load_dwordx2 v[28:29], v[20:21], off offset:124
	global_load_dwordx4 v[12:15], v[248:249], off offset:244
	global_load_dwordx2 v[30:31], v[20:21], off offset:156
	global_load_dwordx4 v[16:19], v[248:249], off offset:308
	global_load_dwordx2 v[46:47], v[20:21], off offset:188
	global_load_dwordx4 v[34:37], v[248:249], off offset:372
	global_load_dwordx2 v[48:49], v[20:21], off offset:220
	global_load_dwordx4 v[38:41], v[248:249], off offset:436
	global_load_dwordx2 v[50:51], v[20:21], off offset:252
	global_load_dwordx4 v[42:45], v[248:249], off offset:500
	s_mov_b32 s2, 0
	s_mov_b64 s[4:5], 0x200
.Lssdn_loop:
	s_waitcnt vmcnt(30)
	v_lshlrev_b32_e32 v164, 16, v144
	v_and_b32_e32 v165, 0xffff0000, v144
	v_mul_f32_e32 v164, v32, v164
	v_mul_f32_e32 v165, v32, v165
	v_mul_f32_e32 v164, v172, v164
	v_mul_f32_e32 v165, v173, v165
	v_cvt_pk_bf16_f32 v166, v164, v165
	v_lshlrev_b32_e32 v164, 16, v145
	v_and_b32_e32 v165, 0xffff0000, v145
	v_mul_f32_e32 v164, v32, v164
	v_mul_f32_e32 v165, v32, v165
	v_mul_f32_e32 v164, v174, v164
	v_mul_f32_e32 v165, v175, v165
	v_cvt_pk_bf16_f32 v167, v164, v165
	s_nop 0
	global_store_dwordx2 v[20:21], v[166:167], off offset:-228
	s_waitcnt vmcnt(29)
	v_lshlrev_b32_e32 v164, 16, v146
	v_and_b32_e32 v165, 0xffff0000, v146
	v_mul_f32_e32 v164, v32, v164
	v_mul_f32_e32 v165, v32, v165
	v_mul_f32_e32 v164, v176, v164
	v_mul_f32_e32 v165, v177, v165
	v_cvt_pk_bf16_f32 v166, v164, v165
	v_lshlrev_b32_e32 v164, 16, v147
	v_and_b32_e32 v165, 0xffff0000, v147
	v_mul_f32_e32 v164, v32, v164
	v_mul_f32_e32 v165, v32, v165
	v_mul_f32_e32 v164, v178, v164
	v_mul_f32_e32 v165, v179, v165
	v_cvt_pk_bf16_f32 v167, v164, v165
	s_nop 0
	global_store_dwordx2 v[20:21], v[166:167], off offset:-196
	s_waitcnt vmcnt(28)
	v_lshlrev_b32_e32 v164, 16, v148
	v_and_b32_e32 v165, 0xffff0000, v148
	v_mul_f32_e32 v164, v32, v164
	v_mul_f32_e32 v165, v32, v165
	v_mul_f32_e32 v164, v180, v164
	v_mul_f32_e32 v165, v181, v165
	v_cvt_pk_bf16_f32 v166, v164, v165
	v_lshlrev_b32_e32 v164, 16, v149
	v_and_b32_e32 v165, 0xffff0000, v149
	v_mul_f32_e32 v164, v32, v164
	v_mul_f32_e32 v165, v32, v165
	v_mul_f32_e32 v164, v182, v164
	v_mul_f32_e32 v165, v183, v165
	v_cvt_pk_bf16_f32 v167, v164, v165
	s_nop 0
	global_store_dwordx2 v[20:21], v[166:167], off offset:-164
	s_waitcnt vmcnt(27)
	v_lshlrev_b32_e32 v164, 16, v150
	v_and_b32_e32 v165, 0xffff0000, v150
	v_mul_f32_e32 v164, v32, v164
	v_mul_f32_e32 v165, v32, v165
	v_mul_f32_e32 v164, v184, v164
	v_mul_f32_e32 v165, v185, v165
	v_cvt_pk_bf16_f32 v166, v164, v165
	v_lshlrev_b32_e32 v164, 16, v151
	v_and_b32_e32 v165, 0xffff0000, v151
	v_mul_f32_e32 v164, v32, v164
	v_mul_f32_e32 v165, v32, v165
	v_mul_f32_e32 v164, v186, v164
	v_mul_f32_e32 v165, v187, v165
	v_cvt_pk_bf16_f32 v167, v164, v165
	s_nop 0
	global_store_dwordx2 v[20:21], v[166:167], off offset:-132
	s_waitcnt vmcnt(26)
	v_lshlrev_b32_e32 v164, 16, v152
	v_and_b32_e32 v165, 0xffff0000, v152
	v_mul_f32_e32 v164, v32, v164
	v_mul_f32_e32 v165, v32, v165
	v_mul_f32_e32 v164, v188, v164
	v_mul_f32_e32 v165, v189, v165
	v_cvt_pk_bf16_f32 v166, v164, v165
	v_lshlrev_b32_e32 v164, 16, v153
	v_and_b32_e32 v165, 0xffff0000, v153
	v_mul_f32_e32 v164, v32, v164
	v_mul_f32_e32 v165, v32, v165
	v_mul_f32_e32 v164, v190, v164
	v_mul_f32_e32 v165, v191, v165
	v_cvt_pk_bf16_f32 v167, v164, v165
	s_nop 0
	global_store_dwordx2 v[20:21], v[166:167], off offset:-100
	s_waitcnt vmcnt(25)
	v_lshlrev_b32_e32 v164, 16, v154
	v_and_b32_e32 v165, 0xffff0000, v154
	v_mul_f32_e32 v164, v32, v164
	v_mul_f32_e32 v165, v32, v165
	v_mul_f32_e32 v164, v236, v164
	v_mul_f32_e32 v165, v237, v165
	v_cvt_pk_bf16_f32 v166, v164, v165
	v_lshlrev_b32_e32 v164, 16, v155
	v_and_b32_e32 v165, 0xffff0000, v155
	v_mul_f32_e32 v164, v32, v164
	v_mul_f32_e32 v165, v32, v165
	v_mul_f32_e32 v164, v238, v164
	v_mul_f32_e32 v165, v239, v165
	v_cvt_pk_bf16_f32 v167, v164, v165
	s_nop 0
	global_store_dwordx2 v[20:21], v[166:167], off offset:-68
	s_waitcnt vmcnt(24)
	v_lshlrev_b32_e32 v164, 16, v156
	v_and_b32_e32 v165, 0xffff0000, v156
	v_mul_f32_e32 v164, v32, v164
	v_mul_f32_e32 v165, v32, v165
	v_mul_f32_e32 v164, v240, v164
	v_mul_f32_e32 v165, v241, v165
	v_cvt_pk_bf16_f32 v166, v164, v165
	v_lshlrev_b32_e32 v164, 16, v157
	v_and_b32_e32 v165, 0xffff0000, v157
	v_mul_f32_e32 v164, v32, v164
	v_mul_f32_e32 v165, v32, v165
	v_mul_f32_e32 v164, v242, v164
	v_mul_f32_e32 v165, v243, v165
	v_cvt_pk_bf16_f32 v167, v164, v165
	s_nop 0
	global_store_dwordx2 v[20:21], v[166:167], off offset:-36
	s_waitcnt vmcnt(23)
; DI unsigned pk2(float lo, float hi) { unsigned r; asm volatile("v_cvt_pk_bf16_f32 %0, %1, %2" : "=v"(r) : "v"(lo), "v"(hi)); return r; }
; DI float bflo(unsigned u) { return __uint_as_float(u << 16); }
; DI float bfhi(unsigned u) { return __uint_as_float(u & 0xffff0000u); }
; DI void ssd_out_unit(const Params& p, int layer, int hf, int bl, int c, unsigned char* shm, int tid, bool dry = false) {
;     ...
;   for (int t0 = 0; t0 < 64; t0 += 8) {
;     uint2 v8[8]; float4 g8[8];
; #pragma unroll
;     for (int q = 0; q < 8; ++q) { v8[q] = *(const uint2*)(zr + 16 * (t0 + q)); g8[q] = *(const float4*)(gn + 16 * (t0 + q) + 4 * fq); }
; #pragma unroll
;     for (int q = 0; q < 8; ++q) {
;       uint2 w; w.x = pk2(bflo(v8[q].x) * rinv * g8[q].x, bfhi(v8[q].x) * rinv * g8[q].y); w.y = pk2(bflo(v8[q].y) * rinv * g8[q].z, bfhi(v8[q].y) * rinv * g8[q].w);
;       *(uint2*)(zr + 16 * (t0 + q)) = w;
;     }
	v_lshlrev_b32_e32 v164, 16, v158
	v_and_b32_e32 v165, 0xffff0000, v158
	v_mul_f32_e32 v164, v32, v164
	v_mul_f32_e32 v165, v32, v165
	v_mul_f32_e32 v164, v244, v164
	v_mul_f32_e32 v165, v245, v165
	v_cvt_pk_bf16_f32 v166, v164, v165
	v_lshlrev_b32_e32 v164, 16, v159
	v_and_b32_e32 v165, 0xffff0000, v159
	v_mul_f32_e32 v164, v32, v164
	v_mul_f32_e32 v165, v32, v165
	v_mul_f32_e32 v164, v246, v164
	v_mul_f32_e32 v165, v247, v165
	v_cvt_pk_bf16_f32 v167, v164, v165
	s_nop 0
	global_store_dwordx2 v[20:21], v[166:167], off offset:-4
	global_load_dwordx2 v[144:145], v[20:21], off offset:284
	global_load_dwordx4 v[172:175], v[248:249], off offset:564
	global_load_dwordx2 v[146:147], v[20:21], off offset:316
	global_load_dwordx4 v[176:179], v[248:249], off offset:628
	global_load_dwordx2 v[148:149], v[20:21], off offset:348
	global_load_dwordx4 v[180:183], v[248:249], off offset:692
	global_load_dwordx2 v[150:151], v[20:21], off offset:380
	global_load_dwordx4 v[184:187], v[248:249], off offset:756
	global_load_dwordx2 v[152:153], v[20:21], off offset:412
	global_load_dwordx4 v[188:191], v[248:249], off offset:820
	global_load_dwordx2 v[154:155], v[20:21], off offset:444
	global_load_dwordx4 v[236:239], v[248:249], off offset:884
	global_load_dwordx2 v[156:157], v[20:21], off offset:476
	global_load_dwordx4 v[240:243], v[248:249], off offset:948
	global_load_dwordx2 v[158:159], v[20:21], off offset:508
	global_load_dwordx4 v[244:247], v[248:249], off offset:1012
	s_waitcnt vmcnt(38)
	v_lshlrev_b32_e32 v164, 16, v22
	v_and_b32_e32 v165, 0xffff0000, v22
	v_mul_f32_e32 v164, v32, v164
	v_mul_f32_e32 v165, v32, v165
	v_mul_f32_e32 v164, v0, v164
	v_mul_f32_e32 v165, v1, v165
	v_cvt_pk_bf16_f32 v166, v164, v165
	v_lshlrev_b32_e32 v164, 16, v23
	v_and_b32_e32 v165, 0xffff0000, v23
	v_mul_f32_e32 v164, v32, v164
	v_mul_f32_e32 v165, v32, v165
	v_mul_f32_e32 v164, v2, v164
	v_mul_f32_e32 v165, v3, v165
	v_cvt_pk_bf16_f32 v167, v164, v165
	s_nop 0
	global_store_dwordx2 v[20:21], v[166:167], off offset:28
	s_waitcnt vmcnt(37)
	v_lshlrev_b32_e32 v164, 16, v24
	v_and_b32_e32 v165, 0xffff0000, v24
	v_mul_f32_e32 v164, v32, v164
	v_mul_f32_e32 v165, v32, v165
	v_mul_f32_e32 v164, v4, v164
	v_mul_f32_e32 v165, v5, v165
	v_cvt_pk_bf16_f32 v166, v164, v165
	v_lshlrev_b32_e32 v164, 16, v25
	v_and_b32_e32 v165, 0xffff0000, v25
	v_mul_f32_e32 v164, v32, v164
	v_mul_f32_e32 v165, v32, v165
	v_mul_f32_e32 v164, v6, v164
	v_mul_f32_e32 v165, v7, v165
	v_cvt_pk_bf16_f32 v167, v164, v165
	s_nop 0
	global_store_dwordx2 v[20:21], v[166:167], off offset:60
	s_waitcnt vmcnt(36)
	v_lshlrev_b32_e32 v164, 16, v26
	v_and_b32_e32 v165, 0xffff0000, v26
	v_mul_f32_e32 v164, v32, v164
	v_mul_f32_e32 v165, v32, v165
	v_mul_f32_e32 v164, v8, v164
	v_mul_f32_e32 v165, v9, v165
	v_cvt_pk_bf16_f32 v166, v164, v165
	v_lshlrev_b32_e32 v164, 16, v27
	v_and_b32_e32 v165, 0xffff0000, v27
	v_mul_f32_e32 v164, v32, v164
	v_mul_f32_e32 v165, v32, v165
	v_mul_f32_e32 v164, v10, v164
	v_mul_f32_e32 v165, v11, v165
	v_cvt_pk_bf16_f32 v167, v164, v165
	s_nop 0
	global_store_dwordx2 v[20:21], v[166:167], off offset:92
	s_waitcnt vmcnt(35)
	v_lshlrev_b32_e32 v164, 16, v28
	v_and_b32_e32 v165, 0xffff0000, v28
	v_mul_f32_e32 v164, v32, v164
	v_mul_f32_e32 v165, v32, v165
	v_mul_f32_e32 v164, v12, v164
	v_mul_f32_e32 v165, v13, v165
	v_cvt_pk_bf16_f32 v166, v164, v165
	v_lshlrev_b32_e32 v164, 16, v29
	v_and_b32_e32 v165, 0xffff0000, v29
	v_mul_f32_e32 v164, v32, v164
	v_mul_f32_e32 v165, v32, v165
	v_mul_f32_e32 v164, v14, v164
	v_mul_f32_e32 v165, v15, v165
	v_cvt_pk_bf16_f32 v167, v164, v165
	s_nop 0
	global_store_dwordx2 v[20:21], v[166:167], off offset:124
	s_waitcnt vmcnt(34)
	v_lshlrev_b32_e32 v164, 16, v30
	v_and_b32_e32 v165, 0xffff0000, v30
	v_mul_f32_e32 v164, v32, v164
	v_mul_f32_e32 v165, v32, v165
	v_mul_f32_e32 v164, v16, v164
	v_mul_f32_e32 v165, v17, v165
	v_cvt_pk_bf16_f32 v166, v164, v165
	v_lshlrev_b32_e32 v164, 16, v31
	v_and_b32_e32 v165, 0xffff0000, v31
	v_mul_f32_e32 v164, v32, v164
	v_mul_f32_e32 v165, v32, v165
	v_mul_f32_e32 v164, v18, v164
	v_mul_f32_e32 v165, v19, v165
	v_cvt_pk_bf16_f32 v167, v164, v165
	s_nop 0
	global_store_dwordx2 v[20:21], v[166:167], off offset:156
	s_waitcnt vmcnt(33)
	v_lshlrev_b32_e32 v164, 16, v46
	v_and_b32_e32 v165, 0xffff0000, v46
	v_mul_f32_e32 v164, v32, v164
	v_mul_f32_e32 v165, v32, v165
	v_mul_f32_e32 v164, v34, v164
	v_mul_f32_e32 v165, v35, v165
	v_cvt_pk_bf16_f32 v166, v164, v165
	v_lshlrev_b32_e32 v164, 16, v47
	v_and_b32_e32 v165, 0xffff0000, v47
	v_mul_f32_e32 v164, v32, v164
	v_mul_f32_e32 v165, v32, v165
	v_mul_f32_e32 v164, v36, v164
	v_mul_f32_e32 v165, v37, v165
	v_cvt_pk_bf16_f32 v167, v164, v165
	s_nop 0
	global_store_dwordx2 v[20:21], v[166:167], off offset:188
	s_waitcnt vmcnt(32)
	v_lshlrev_b32_e32 v164, 16, v48
	v_and_b32_e32 v165, 0xffff0000, v48
	v_mul_f32_e32 v164, v32, v164
	v_mul_f32_e32 v165, v32, v165
	v_mul_f32_e32 v164, v38, v164
	v_mul_f32_e32 v165, v39, v165
	v_cvt_pk_bf16_f32 v166, v164, v165
	v_lshlrev_b32_e32 v164, 16, v49
	v_and_b32_e32 v165, 0xffff0000, v49
	v_mul_f32_e32 v164, v32, v164
	v_mul_f32_e32 v165, v32, v165
	v_mul_f32_e32 v164, v40, v164
	v_mul_f32_e32 v165, v41, v165
	v_cvt_pk_bf16_f32 v167, v164, v165
	s_nop 0
	global_store_dwordx2 v[20:21], v[166:167], off offset:220
	s_waitcnt vmcnt(31)
	v_lshlrev_b32_e32 v164, 16, v50
	v_and_b32_e32 v165, 0xffff0000, v50
	v_mul_f32_e32 v164, v32, v164
	v_mul_f32_e32 v165, v32, v165
	v_mul_f32_e32 v164, v42, v164
	v_mul_f32_e32 v165, v43, v165
	v_cvt_pk_bf16_f32 v166, v164, v165
	v_lshlrev_b32_e32 v164, 16, v51
	v_and_b32_e32 v165, 0xffff0000, v51
	v_mul_f32_e32 v164, v32, v164
	v_mul_f32_e32 v165, v32, v165
	v_mul_f32_e32 v164, v44, v164
	v_mul_f32_e32 v165, v45, v165
	v_cvt_pk_bf16_f32 v167, v164, v165
	s_nop 0
	global_store_dwordx2 v[20:21], v[166:167], off offset:252
	global_load_dwordx2 v[22:23], v[20:21], off offset:540
	global_load_dwordx4 v[0:3], v[248:249], off offset:1076
	global_load_dwordx2 v[24:25], v[20:21], off offset:572
	global_load_dwordx4 v[4:7], v[248:249], off offset:1140
	global_load_dwordx2 v[26:27], v[20:21], off offset:604
	global_load_dwordx4 v[8:11], v[248:249], off offset:1204
	global_load_dwordx2 v[28:29], v[20:21], off offset:636
	global_load_dwordx4 v[12:15], v[248:249], off offset:1268
	global_load_dwordx2 v[30:31], v[20:21], off offset:668
	global_load_dwordx4 v[16:19], v[248:249], off offset:1332
	global_load_dwordx2 v[46:47], v[20:21], off offset:700
	global_load_dwordx4 v[34:37], v[248:249], off offset:1396
	global_load_dwordx2 v[48:49], v[20:21], off offset:732
	global_load_dwordx4 v[38:41], v[248:249], off offset:1460
	global_load_dwordx2 v[50:51], v[20:21], off offset:764
	global_load_dwordx4 v[42:45], v[248:249], off offset:1524
	v_lshl_add_u64 v[20:21], v[20:21], 0, s[4:5]
	v_lshl_add_u64 v[248:249], v[248:249], 0, s[4:5]
	v_lshl_add_u64 v[248:249], v[248:249], 0, s[4:5]
	s_add_i32 s2, s2, 1
	s_cmp_lt_u32 s2, 3
	s_cbranch_scc1 .Lssdn_loop
; DI unsigned pk2(float lo, float hi) { unsigned r; asm volatile("v_cvt_pk_bf16_f32 %0, %1, %2" : "=v"(r) : "v"(lo), "v"(hi)); return r; }
; DI float bflo(unsigned u) { return __uint_as_float(u << 16); }
; DI float bfhi(unsigned u) { return __uint_as_float(u & 0xffff0000u); }
; DI void ssd_out_unit(const Params& p, int layer, int hf, int bl, int c, unsigned char* shm, int tid, bool dry = false) {
;     ...
; #pragma unroll
;     for (int q = 0; q < 8; ++q) {
;       uint2 w; w.x = pk2(bflo(v8[q].x) * rinv * g8[q].x, bfhi(v8[q].x) * rinv * g8[q].y); w.y = pk2(bflo(v8[q].y) * rinv * g8[q].z, bfhi(v8[q].y) * rinv * g8[q].w);
;       *(uint2*)(zr + 16 * (t0 + q)) = w;
;     }
	s_waitcnt vmcnt(38)
	v_lshlrev_b32_e32 v164, 16, v144
	v_and_b32_e32 v165, 0xffff0000, v144
	v_mul_f32_e32 v164, v32, v164
	v_mul_f32_e32 v165, v32, v165
	v_mul_f32_e32 v164, v172, v164
	v_mul_f32_e32 v165, v173, v165
	v_cvt_pk_bf16_f32 v166, v164, v165
	v_lshlrev_b32_e32 v164, 16, v145
	v_and_b32_e32 v165, 0xffff0000, v145
	v_mul_f32_e32 v164, v32, v164
	v_mul_f32_e32 v165, v32, v165
	v_mul_f32_e32 v164, v174, v164
	v_mul_f32_e32 v165, v175, v165
	v_cvt_pk_bf16_f32 v167, v164, v165
	s_nop 0
	global_store_dwordx2 v[20:21], v[166:167], off offset:-228
	s_waitcnt vmcnt(37)
	v_lshlrev_b32_e32 v164, 16, v146
	v_and_b32_e32 v165, 0xffff0000, v146
	v_mul_f32_e32 v164, v32, v164
	v_mul_f32_e32 v165, v32, v165
	v_mul_f32_e32 v164, v176, v164
	v_mul_f32_e32 v165, v177, v165
	v_cvt_pk_bf16_f32 v166, v164, v165
	v_lshlrev_b32_e32 v164, 16, v147
	v_and_b32_e32 v165, 0xffff0000, v147
	v_mul_f32_e32 v164, v32, v164
	v_mul_f32_e32 v165, v32, v165
	v_mul_f32_e32 v164, v178, v164
	v_mul_f32_e32 v165, v179, v165
	v_cvt_pk_bf16_f32 v167, v164, v165
	s_nop 0
	global_store_dwordx2 v[20:21], v[166:167], off offset:-196
	s_waitcnt vmcnt(36)
	v_lshlrev_b32_e32 v164, 16, v148
	v_and_b32_e32 v165, 0xffff0000, v148
	v_mul_f32_e32 v164, v32, v164
	v_mul_f32_e32 v165, v32, v165
	v_mul_f32_e32 v164, v180, v164
	v_mul_f32_e32 v165, v181, v165
	v_cvt_pk_bf16_f32 v166, v164, v165
	v_lshlrev_b32_e32 v164, 16, v149
	v_and_b32_e32 v165, 0xffff0000, v149
	v_mul_f32_e32 v164, v32, v164
	v_mul_f32_e32 v165, v32, v165
	v_mul_f32_e32 v164, v182, v164
	v_mul_f32_e32 v165, v183, v165
	v_cvt_pk_bf16_f32 v167, v164, v165
	s_nop 0
	global_store_dwordx2 v[20:21], v[166:167], off offset:-164
	s_waitcnt vmcnt(35)
	v_lshlrev_b32_e32 v164, 16, v150
	v_and_b32_e32 v165, 0xffff0000, v150
	v_mul_f32_e32 v164, v32, v164
	v_mul_f32_e32 v165, v32, v165
	v_mul_f32_e32 v164, v184, v164
	v_mul_f32_e32 v165, v185, v165
	v_cvt_pk_bf16_f32 v166, v164, v165
	v_lshlrev_b32_e32 v164, 16, v151
	v_and_b32_e32 v165, 0xffff0000, v151
	v_mul_f32_e32 v164, v32, v164
	v_mul_f32_e32 v165, v32, v165
	v_mul_f32_e32 v164, v186, v164
	v_mul_f32_e32 v165, v187, v165
	v_cvt_pk_bf16_f32 v167, v164, v165
	s_nop 0
	global_store_dwordx2 v[20:21], v[166:167], off offset:-132
	s_waitcnt vmcnt(34)
	v_lshlrev_b32_e32 v164, 16, v152
	v_and_b32_e32 v165, 0xffff0000, v152
	v_mul_f32_e32 v164, v32, v164
	v_mul_f32_e32 v165, v32, v165
	v_mul_f32_e32 v164, v188, v164
	v_mul_f32_e32 v165, v189, v165
	v_cvt_pk_bf16_f32 v166, v164, v165
	v_lshlrev_b32_e32 v164, 16, v153
	v_and_b32_e32 v165, 0xffff0000, v153
	v_mul_f32_e32 v164, v32, v164
	v_mul_f32_e32 v165, v32, v165
	v_mul_f32_e32 v164, v190, v164
	v_mul_f32_e32 v165, v191, v165
	v_cvt_pk_bf16_f32 v167, v164, v165
	s_nop 0
	global_store_dwordx2 v[20:21], v[166:167], off offset:-100
	s_waitcnt vmcnt(33)
	v_lshlrev_b32_e32 v164, 16, v154
	v_and_b32_e32 v165, 0xffff0000, v154
	v_mul_f32_e32 v164, v32, v164
	v_mul_f32_e32 v165, v32, v165
	v_mul_f32_e32 v164, v236, v164
	v_mul_f32_e32 v165, v237, v165
	v_cvt_pk_bf16_f32 v166, v164, v165
	v_lshlrev_b32_e32 v164, 16, v155
	v_and_b32_e32 v165, 0xffff0000, v155
	v_mul_f32_e32 v164, v32, v164
	v_mul_f32_e32 v165, v32, v165
	v_mul_f32_e32 v164, v238, v164
	v_mul_f32_e32 v165, v239, v165
	v_cvt_pk_bf16_f32 v167, v164, v165
	s_nop 0
	global_store_dwordx2 v[20:21], v[166:167], off offset:-68
	s_waitcnt vmcnt(32)
	v_lshlrev_b32_e32 v164, 16, v156
	v_and_b32_e32 v165, 0xffff0000, v156
	v_mul_f32_e32 v164, v32, v164
	v_mul_f32_e32 v165, v32, v165
	v_mul_f32_e32 v164, v240, v164
	v_mul_f32_e32 v165, v241, v165
	v_cvt_pk_bf16_f32 v166, v164, v165
	v_lshlrev_b32_e32 v164, 16, v157
	v_and_b32_e32 v165, 0xffff0000, v157
	v_mul_f32_e32 v164, v32, v164
	v_mul_f32_e32 v165, v32, v165
	v_mul_f32_e32 v164, v242, v164
	v_mul_f32_e32 v165, v243, v165
	v_cvt_pk_bf16_f32 v167, v164, v165
	s_nop 0
	global_store_dwordx2 v[20:21], v[166:167], off offset:-36
	s_waitcnt vmcnt(31)
	v_lshlrev_b32_e32 v164, 16, v158
	v_and_b32_e32 v165, 0xffff0000, v158
	v_mul_f32_e32 v164, v32, v164
	v_mul_f32_e32 v165, v32, v165
	v_mul_f32_e32 v164, v244, v164
	v_mul_f32_e32 v165, v245, v165
	v_cvt_pk_bf16_f32 v166, v164, v165
	v_lshlrev_b32_e32 v164, 16, v159
	v_and_b32_e32 v165, 0xffff0000, v159
	v_mul_f32_e32 v164, v32, v164
	v_mul_f32_e32 v165, v32, v165
	v_mul_f32_e32 v164, v246, v164
	v_mul_f32_e32 v165, v247, v165
	v_cvt_pk_bf16_f32 v167, v164, v165
	s_nop 0
	global_store_dwordx2 v[20:21], v[166:167], off offset:-4
	s_waitcnt vmcnt(22)
; DI unsigned pk2(float lo, float hi) { unsigned r; asm volatile("v_cvt_pk_bf16_f32 %0, %1, %2" : "=v"(r) : "v"(lo), "v"(hi)); return r; }
; DI float bflo(unsigned u) { return __uint_as_float(u << 16); }
; DI float bfhi(unsigned u) { return __uint_as_float(u & 0xffff0000u); }
; DI void ssd_out_unit(const Params& p, int layer, int hf, int bl, int c, unsigned char* shm, int tid, bool dry = false) {
;     ...
; #pragma unroll
;     for (int q = 0; q < 8; ++q) {
;       uint2 w; w.x = pk2(bflo(v8[q].x) * rinv * g8[q].x, bfhi(v8[q].x) * rinv * g8[q].y); w.y = pk2(bflo(v8[q].y) * rinv * g8[q].z, bfhi(v8[q].y) * rinv * g8[q].w);
;       *(uint2*)(zr + 16 * (t0 + q)) = w;
;     }
;   }
;   __syncthreads();
	v_lshlrev_b32_e32 v164, 16, v22
	v_and_b32_e32 v165, 0xffff0000, v22
	v_mul_f32_e32 v164, v32, v164
	v_mul_f32_e32 v165, v32, v165
	v_mul_f32_e32 v164, v0, v164
	v_mul_f32_e32 v165, v1, v165
	v_cvt_pk_bf16_f32 v166, v164, v165
	v_lshlrev_b32_e32 v164, 16, v23
	v_and_b32_e32 v165, 0xffff0000, v23
	v_mul_f32_e32 v164, v32, v164
	v_mul_f32_e32 v165, v32, v165
	v_mul_f32_e32 v164, v2, v164
	v_mul_f32_e32 v165, v3, v165
	v_cvt_pk_bf16_f32 v167, v164, v165
	s_nop 0
	global_store_dwordx2 v[20:21], v[166:167], off offset:28
	s_waitcnt vmcnt(21)
	v_lshlrev_b32_e32 v164, 16, v24
	v_and_b32_e32 v165, 0xffff0000, v24
	v_mul_f32_e32 v164, v32, v164
	v_mul_f32_e32 v165, v32, v165
	v_mul_f32_e32 v164, v4, v164
	v_mul_f32_e32 v165, v5, v165
	v_cvt_pk_bf16_f32 v166, v164, v165
	v_lshlrev_b32_e32 v164, 16, v25
	v_and_b32_e32 v165, 0xffff0000, v25
	v_mul_f32_e32 v164, v32, v164
	v_mul_f32_e32 v165, v32, v165
	v_mul_f32_e32 v164, v6, v164
	v_mul_f32_e32 v165, v7, v165
	v_cvt_pk_bf16_f32 v167, v164, v165
	s_nop 0
	global_store_dwordx2 v[20:21], v[166:167], off offset:60
	s_waitcnt vmcnt(20)
	v_lshlrev_b32_e32 v164, 16, v26
	v_and_b32_e32 v165, 0xffff0000, v26
	v_mul_f32_e32 v164, v32, v164
	v_mul_f32_e32 v165, v32, v165
	v_mul_f32_e32 v164, v8, v164
	v_mul_f32_e32 v165, v9, v165
	v_cvt_pk_bf16_f32 v166, v164, v165
	v_lshlrev_b32_e32 v164, 16, v27
	v_and_b32_e32 v165, 0xffff0000, v27
	v_mul_f32_e32 v164, v32, v164
	v_mul_f32_e32 v165, v32, v165
	v_mul_f32_e32 v164, v10, v164
	v_mul_f32_e32 v165, v11, v165
	v_cvt_pk_bf16_f32 v167, v164, v165
	s_nop 0
	global_store_dwordx2 v[20:21], v[166:167], off offset:92
	s_waitcnt vmcnt(19)
	v_lshlrev_b32_e32 v164, 16, v28
	v_and_b32_e32 v165, 0xffff0000, v28
	v_mul_f32_e32 v164, v32, v164
	v_mul_f32_e32 v165, v32, v165
	v_mul_f32_e32 v164, v12, v164
	v_mul_f32_e32 v165, v13, v165
	v_cvt_pk_bf16_f32 v166, v164, v165
	v_lshlrev_b32_e32 v164, 16, v29
	v_and_b32_e32 v165, 0xffff0000, v29
	v_mul_f32_e32 v164, v32, v164
	v_mul_f32_e32 v165, v32, v165
	v_mul_f32_e32 v164, v14, v164
	v_mul_f32_e32 v165, v15, v165
	v_cvt_pk_bf16_f32 v167, v164, v165
	s_nop 0
	global_store_dwordx2 v[20:21], v[166:167], off offset:124
	s_waitcnt vmcnt(18)
	v_lshlrev_b32_e32 v164, 16, v30
	v_and_b32_e32 v165, 0xffff0000, v30
	v_mul_f32_e32 v164, v32, v164
	v_mul_f32_e32 v165, v32, v165
	v_mul_f32_e32 v164, v16, v164
	v_mul_f32_e32 v165, v17, v165
	v_cvt_pk_bf16_f32 v166, v164, v165
	v_lshlrev_b32_e32 v164, 16, v31
	v_and_b32_e32 v165, 0xffff0000, v31
	v_mul_f32_e32 v164, v32, v164
	v_mul_f32_e32 v165, v32, v165
	v_mul_f32_e32 v164, v18, v164
	v_mul_f32_e32 v165, v19, v165
	v_cvt_pk_bf16_f32 v167, v164, v165
	s_nop 0
	global_store_dwordx2 v[20:21], v[166:167], off offset:156
	s_waitcnt vmcnt(17)
	v_lshlrev_b32_e32 v164, 16, v46
	v_and_b32_e32 v165, 0xffff0000, v46
	v_mul_f32_e32 v164, v32, v164
	v_mul_f32_e32 v165, v32, v165
	v_mul_f32_e32 v164, v34, v164
	v_mul_f32_e32 v165, v35, v165
	v_cvt_pk_bf16_f32 v166, v164, v165
	v_lshlrev_b32_e32 v164, 16, v47
	v_and_b32_e32 v165, 0xffff0000, v47
	v_mul_f32_e32 v164, v32, v164
	v_mul_f32_e32 v165, v32, v165
	v_mul_f32_e32 v164, v36, v164
	v_mul_f32_e32 v165, v37, v165
	v_cvt_pk_bf16_f32 v167, v164, v165
	s_nop 0
	global_store_dwordx2 v[20:21], v[166:167], off offset:188
	s_waitcnt vmcnt(16)
	v_lshlrev_b32_e32 v164, 16, v48
	v_and_b32_e32 v165, 0xffff0000, v48
	v_mul_f32_e32 v164, v32, v164
	v_mul_f32_e32 v165, v32, v165
	v_mul_f32_e32 v164, v38, v164
	v_mul_f32_e32 v165, v39, v165
	v_cvt_pk_bf16_f32 v166, v164, v165
	v_lshlrev_b32_e32 v164, 16, v49
	v_and_b32_e32 v165, 0xffff0000, v49
	v_mul_f32_e32 v164, v32, v164
	v_mul_f32_e32 v165, v32, v165
	v_mul_f32_e32 v164, v40, v164
	v_mul_f32_e32 v165, v41, v165
	v_cvt_pk_bf16_f32 v167, v164, v165
	s_nop 0
	global_store_dwordx2 v[20:21], v[166:167], off offset:220
	s_waitcnt vmcnt(15)
	v_lshlrev_b32_e32 v164, 16, v50
	v_and_b32_e32 v165, 0xffff0000, v50
	v_mul_f32_e32 v164, v32, v164
	v_mul_f32_e32 v165, v32, v165
	v_mul_f32_e32 v164, v42, v164
	v_mul_f32_e32 v165, v43, v165
	v_cvt_pk_bf16_f32 v166, v164, v165
	v_lshlrev_b32_e32 v164, 16, v51
	v_and_b32_e32 v165, 0xffff0000, v51
	v_mul_f32_e32 v164, v32, v164
	v_mul_f32_e32 v165, v32, v165
	v_mul_f32_e32 v164, v44, v164
	v_mul_f32_e32 v165, v45, v165
	v_cvt_pk_bf16_f32 v167, v164, v165
	s_nop 0
	global_store_dwordx2 v[20:21], v[166:167], off offset:252
	v_readlane_b32 s62, v254, 16
	v_readlane_b32 s61, v254, 15
	v_readlane_b32 s63, v254, 17
	v_readlane_b32 s33, v254, 18
	v_readlane_b32 s64, v254, 19
	s_movk_i32 s66, 0x110
	s_movk_i32 s67, 0xc00
	v_readlane_b32 s68, v255, 2
	v_readlane_b32 s23, v254, 63
	s_barrier
